# grid barrier: waiting workgroups poll the top-level generation word directly (one forwarding hop less per barrier)
# baseline (speedup 1.0000x reference)
.LBB0_880:
	s_or_b64 exec, exec, s[6:7]
	v_cvt_f32_u32_e32 v5, v3
	s_waitcnt vmcnt(0)
	v_readfirstlane_b32 s4, v4
	v_sub_u32_e32 v4, 0, v3
	v_rcp_iflag_f32_e32 v5, v5
	v_add_u32_e32 v6, s4, v0
	v_mul_f32_e32 v5, 0x4f7ffffe, v5
	v_cvt_u32_f32_e32 v5, v5
	v_mul_lo_u32 v0, v4, v5
	v_mul_hi_u32 v0, v5, v0
	v_add_u32_e32 v0, v5, v0
	v_mul_hi_u32 v0, v6, v0
	v_mul_lo_u32 v4, v0, v3
	v_sub_u32_e32 v4, v6, v4
	v_add_u32_e32 v5, 1, v0
	v_cmp_ge_u32_e32 vcc, v4, v3
	s_nop 1
	v_cndmask_b32_e32 v0, v0, v5, vcc
	v_sub_u32_e32 v5, v4, v3
	v_cndmask_b32_e32 v4, v4, v5, vcc
	v_add_u32_e32 v5, 1, v0
	v_cmp_ge_u32_e32 vcc, v4, v3
	v_add_u32_e32 v4, 1, v6
	s_nop 0
	v_cndmask_b32_e32 v0, v0, v5, vcc
	v_mul_lo_u32 v5, v3, v0
	v_add_u32_e32 v3, v5, v3
	v_cmp_ne_u32_e32 vcc, v4, v3
	s_and_saveexec_b64 s[4:5], vcc
	s_xor_b64 s[4:5], exec, s[4:5]
	s_cbranch_execz .LBB0_894
	s_waitcnt lgkmcnt(0)
	v_readlane_b32 s8, v252, 12
	v_readlane_b32 s9, v252, 13
	s_nop 4
	global_load_dword v2, v1, s[8:9] sc1
	s_waitcnt vmcnt(0)
	v_cmp_eq_u32_e32 vcc, v2, v0
	s_and_saveexec_b64 s[6:7], vcc
	s_cbranch_execz .LBB0_893
	s_mov_b32 s20, 1
	s_mov_b64 s[10:11], 0
	s_branch .LBB0_884
